# v13 + same invalidate trim at grid-sync exit 197 + barrier-pointer s_load issued before the L2 write-back wait at 9 sync entries
# baseline (speedup 1.0000x reference)
; __device__ __forceinline__ void grid_sync(cg::grid_group& grid) {
;     asm volatile("s_waitcnt vmcnt(0) lgkmcnt(0)" ::: "memory"); grid.sync();
;     __builtin_amdgcn_fence(__ATOMIC_ACQUIRE, "agent"); asm volatile("s_waitcnt vmcnt(0)" ::: "memory"); }
.LBB0_161:
	s_waitcnt vmcnt(0) lgkmcnt(0)
	s_waitcnt lgkmcnt(0)
	s_barrier
	s_mov_b64 s[2:3], exec
	v_readlane_b32 s4, v253, 60
	v_readlane_b32 s5, v253, 61
	s_and_b64 s[4:5], s[2:3], s[4:5]
	s_mov_b64 exec, s[4:5]
	s_cbranch_execz .LBB0_171
	v_readlane_b32 s4, v249, 0
	v_readlane_b32 s5, v249, 1
	buffer_wbl2 sc1
	s_load_dwordx2 s[4:5], s[4:5], 0x58
	s_waitcnt vmcnt(0)
	s_mov_b64 s[6:7], exec
	v_mbcnt_lo_u32_b32 v1, s6, 0
	v_mbcnt_hi_u32_b32 v1, s7, v1
	v_cmp_eq_u32_e32 vcc, 0, v1
	s_waitcnt lgkmcnt(0)
	global_load_dword v0, v153, s[4:5] offset:40
	s_and_saveexec_b64 s[8:9], vcc
	s_cbranch_execz .LBB0_164
	s_bcnt1_i32_b64 s6, s[6:7]
	v_mov_b32_e32 v2, s6
	global_atomic_add v2, v153, v2, s[4:5] offset:32 sc0

; __device__ __forceinline__ void grid_sync(cg::grid_group& grid) {
;     asm volatile("s_waitcnt vmcnt(0) lgkmcnt(0)" ::: "memory"); grid.sync();
;     __builtin_amdgcn_fence(__ATOMIC_ACQUIRE, "agent"); asm volatile("s_waitcnt vmcnt(0)" ::: "memory"); }
.LBB0_187:
	s_waitcnt vmcnt(0) lgkmcnt(0)
	s_barrier
	s_mov_b64 s[2:3], exec
	v_readlane_b32 s4, v253, 60
	v_readlane_b32 s5, v253, 61
	s_and_b64 s[4:5], s[2:3], s[4:5]
	s_mov_b32 s89, s11
	s_mov_b64 exec, s[4:5]
	s_cbranch_execz .LBB0_197
	v_readlane_b32 s4, v249, 0
	v_readlane_b32 s5, v249, 1
	buffer_wbl2 sc1
	s_load_dwordx2 s[4:5], s[4:5], 0x58
	s_waitcnt vmcnt(0)
	s_mov_b64 s[6:7], exec
	v_mbcnt_lo_u32_b32 v1, s6, 0
	v_mbcnt_hi_u32_b32 v1, s7, v1
	v_cmp_eq_u32_e32 vcc, 0, v1
	s_waitcnt lgkmcnt(0)
	global_load_dword v0, v153, s[4:5] offset:40
	s_and_saveexec_b64 s[8:9], vcc
	s_cbranch_execz .LBB0_190
	s_bcnt1_i32_b64 s6, s[6:7]
	v_mov_b32_e32 v2, s6
	global_atomic_add v2, v153, v2, s[4:5] offset:32 sc0

; #define GB_H16(g)  ((h16*)gbuf(ws, g, OFF_H16, 2048))
; #define PG8_BAR __builtin_amdgcn_s_barrier()
; template <class Epi>
; __device__ __forceinline__ void gemm_phase(LAS unsigned char* lds, const Gemm g, const StaticOrder& S, const Epi& E, const int tid) {
;     const int wid = __builtin_amdgcn_readfirstlane(tid >> 6), lane = tid & 63, wr = wid >> 2, wc = wid & 3, fr = lane & 15, fq = lane >> 4;
;     const int K = g.K, nt = K / BK, lda = g.lda;
;     unsigned voffA[2], voffB[2];
; #pragma unroll
;     for (int i = 0; i < 2; ++i) { int R, C; stage_rc(tid * 16 + i * 8192, R, C); const int Rb = Epi::PERM ? ((R & ~31) + perm32(R & 31)) : R;
;         voffA[i] = (unsigned)(R * lda + C) * 2u; voffB[i] = (unsigned)(Rb * K + C) * 2u; }
;     const size_t kstep = (size_t)(BK * 2);
;     const size_t hstepA = (size_t)HALF * lda * 2, hstepB = (size_t)HALF * K * 2;
;     const size_t tstepA = 2 * hstepA, tstepB = 2 * hstepB;
;     const unsigned ldsw = (unsigned)wid * 1024u;
;     const int aoff = lds_byte(wr * 64 + fr, fq * 8), boff = lds_byte(wc * 32 + fr, fq * 8);
;     ...
;     Unit cur, nxt; int ui = 0;
;     if (!S.next(0, cur)) return;
;     f32x4 acc[2][2][4][2];
; #pragma unroll
;     for (int a = 0; a < 2; ++a)
; #pragma unroll
;         for (int b = 0; b < 2; ++b)
; #pragma unroll
;             for (int m = 0; m < 4; ++m)
; #pragma unroll
;                 for (int n = 0; n < 2; ++n) acc[a][b][m][n] = (f32x4){0.f, 0.f, 0.f, 0.f};
;     h16x8 At[4][2], B0[2][2], B1[2][2];
;     const char* cA = (const char*)g.A + (size_t)cur.pm * tstepA; const char* cB = (const char*)g.Bt + (size_t)cur.pn * tstepB;
;     PG8_STAGE(PG8_SB(0, 0), cB, voffB); PG8_STAGE(PG8_SB(0, 1), cB + hstepB, voffB); PG8_STAGE(PG8_SA(0, 0), cA, voffA); PG8_STAGE(PG8_SA(0, 1), cA + hstepA, voffA);
;     if (wr == 1) PG8_BAR;
;     PG8_WAIT_V(2); PG8_BAR;
; __device__ __forceinline__ void st_ffn_down(STAGE_ARGS, int which) {
;     FRESH_TID unsigned char* ws = args.ws; const h16* W = (const h16*)(ws + WS_W); float* out = args.out;
;     const bool first = (which == 0 && layer == 0);
;     const float* rp = first ? args.in[I_XP] : (const float*)out; const float* rsm = first ? args.in[I_XS] - (size_t)MP * D : (const float*)out;
;     pg8::EpiResid E{rp, rsm, out, GB_H16(g), (float*)(ws + WS_SSA), 0.5f};
;     run_gemm(lds, GB_ACT(g), FF, W + (which ? W_FFN2D : W_FFN1D), D, FF, g, nb, cb, E, tid);
.LBB0_196:
.LBB0_197:
	s_or_b64 exec, exec, s[2:3]
	v_readlane_b32 s4, v248, 0
	v_readlane_b32 s8, v248, 4
	v_readlane_b32 s9, v248, 5
	v_readlane_b32 s10, v248, 6
	v_readlane_b32 s11, v248, 7
	v_readlane_b32 s12, v248, 8
	v_readlane_b32 s13, v248, 9
	v_readlane_b32 s14, v248, 10
	v_readlane_b32 s15, v248, 11
	v_readlane_b32 s16, v248, 12
	v_readlane_b32 s17, v248, 13
	v_readlane_b32 s18, v248, 14
	v_readlane_b32 s19, v248, 15
	s_and_b64 s[2:3], s[44:45], exec
	v_readlane_b32 s8, v248, 48
	v_readlane_b32 s23, v248, 63
	v_readlane_b32 s2, v249, 16
	v_readlane_b32 s22, v248, 62
	s_cselect_b32 s26, s2, s23
	v_readlane_b32 s2, v249, 15
	s_cselect_b32 s27, s2, s22
	v_readlane_b32 s2, v249, 17
	v_readlane_b32 s3, v249, 18
	v_readlane_b32 s5, v248, 1
	s_barrier
	v_cndmask_b32_e64 v1, 0, 1, s[2:3]
	s_waitcnt vmcnt(0)
	buffer_inv sc1
	s_waitcnt vmcnt(0)
	s_cselect_b32 s24, s5, s23
	s_cselect_b32 s25, s4, s22
	v_cmp_ne_u32_e64 s[4:5], 1, v1
	v_mov_b32_e32 v0, v199
	s_andn2_b64 vcc, exec, s[2:3]
	v_writelane_b32 v254, s4, 42
	v_readfirstlane_b32 s2, v0
	v_readlane_b32 s6, v248, 2
	v_writelane_b32 v254, s5, 43
	v_readlane_b32 s7, v248, 3
	v_readlane_b32 s9, v248, 49
	v_readlane_b32 s10, v248, 50
	v_readlane_b32 s11, v248, 51
	v_readlane_b32 s12, v248, 52
	v_readlane_b32 s13, v248, 53
	v_readlane_b32 s14, v248, 54
	v_readlane_b32 s15, v248, 55
	v_readlane_b32 s16, v248, 56
	v_readlane_b32 s17, v248, 57
	v_readlane_b32 s18, v248, 58
	v_readlane_b32 s19, v248, 59
	v_readlane_b32 s20, v248, 60
	v_readlane_b32 s21, v248, 61
	s_cbranch_vccnz .LBB0_237
	v_lshlrev_b32_e32 v5, 4, v0
	v_add_u32_e32 v2, 0x2000, v5
	v_ashrrev_i32_e32 v1, 31, v2
	v_lshrrev_b32_e32 v1, 22, v1
	v_add_u32_e32 v1, v2, v1
	v_ashrrev_i32_e32 v1, 10, v1
	v_mul_i32_i24_e32 v3, 0x400, v1
	v_sub_u32_e32 v2, v2, v3
	v_lshrrev_b32_e32 v3, 4, v2
	v_bitop3_b32 v4, v3, v2, 32 bitop3:0x6c
	v_ashrrev_i32_e32 v2, 31, v4
	v_lshrrev_b32_e32 v2, 26, v2
	v_add_u32_e32 v6, v4, v2
	v_ashrrev_i32_e32 v2, 6, v6
	v_and_b32_e32 v6, 0xc0, v6
	v_sub_u32_e32 v4, v4, v6
	v_bfe_i32 v6, v0, 27, 1
	v_lshrrev_b32_e32 v6, 22, v6
	v_add_u32_e32 v6, v5, v6
	v_and_b32_e32 v6, 0xfffffc00, v6
	v_lshlrev_b32_e32 v3, 3, v1
	v_sub_u32_e32 v5, v5, v6
	v_and_b32_e32 v3, 0xfffff0, v3
	v_lshrrev_b32_e32 v6, 4, v5
	v_add_u32_e32 v3, v2, v3
	s_movk_i32 s4, 0xb00
	v_bitop3_b32 v8, v6, v5, 32 bitop3:0x6c
	v_ashrrev_i32_e32 v6, 31, v0
	v_mul_lo_u32 v7, v3, s4
	v_lshlrev_b32_e32 v3, 5, v1
	v_mov_b32_e32 v11, 1
	v_lshrrev_b32_e32 v6, 26, v6
	v_and_b32_e32 v3, 32, v3
	v_ashrrev_i16_sdwa v4, v11, sext(v4) dst_sel:DWORD dst_unused:UNUSED_PAD src0_sel:DWORD src1_sel:BYTE_0
	v_ashrrev_i32_e32 v5, 31, v8
	v_add_u32_e32 v6, v0, v6
	v_or_b32_e32 v7, v7, v3
	v_bfe_i32 v4, v4, 0, 16
	v_lshrrev_b32_e32 v5, 26, v5
	v_ashrrev_i32_e32 v6, 6, v6
	v_add_lshl_u32 v170, v7, v4, 1
	v_add_u32_e32 v9, v8, v5
	v_lshlrev_b32_e32 v7, 3, v6
	v_ashrrev_i32_e32 v5, 6, v9
	v_and_b32_e32 v7, 0xfffff0, v7
	v_add_u32_e32 v7, v5, v7
	v_and_b32_e32 v9, 0xc0, v9
	s_ashr_i32 s3, s2, 6
	v_mul_lo_u32 v10, v7, s4
	v_lshlrev_b32_e32 v7, 5, v6
	v_sub_u32_e32 v8, v8, v9
	s_lshl_b32 s28, s3, 10
	v_and_b32_e32 v7, 32, v7
	v_ashrrev_i16_sdwa v8, v11, sext(v8) dst_sel:DWORD dst_unused:UNUSED_PAD src0_sel:DWORD src1_sel:BYTE_0
	v_or_b32_e32 v10, v10, v7
	v_bfe_i32 v8, v8, 0, 16
	s_add_i32 s29, s28, 0
	v_readlane_b32 s4, v251, 6
	v_add_lshl_u32 v152, v10, v8, 1
	s_add_i32 m0, s29, 0x10000
	v_readlane_b32 s5, v251, 7
	s_add_i32 s34, s29, 0x2000
	s_add_i32 s35, s29, 0x4000
	s_add_i32 s36, s29, 0x6000
	s_ashr_i32 s6, s2, 8
	s_nop 0
	global_load_lds_dwordx4 v152, s[4:5]
	s_add_i32 m0, s29, 0x12000
	s_nop 0
	global_load_lds_dwordx4 v170, s[4:5]
	v_readlane_b32 s4, v250, 62
	s_add_i32 m0, s29, 0x14000
	v_readlane_b32 s5, v250, 63
	s_nop 4
	global_load_lds_dwordx4 v152, s[4:5]
	s_add_i32 m0, s29, 0x16000
	s_cmp_eq_u32 s6, 1
	global_load_lds_dwordx4 v170, s[4:5]
	v_readlane_b32 s4, v251, 2
	s_mov_b32 m0, s29
	v_readlane_b32 s5, v251, 3
	s_nop 4
	global_load_lds_dwordx4 v152, s[4:5]
	s_mov_b32 m0, s34
	s_nop 0
	global_load_lds_dwordx4 v170, s[4:5]
	v_readlane_b32 s4, v251, 4
	s_mov_b32 m0, s35
	v_readlane_b32 s5, v251, 5
	s_nop 4
	global_load_lds_dwordx4 v152, s[4:5]
	s_mov_b32 m0, s36
	s_nop 0
	global_load_lds_dwordx4 v170, s[4:5]
	s_cselect_b64 s[4:5], -1, 0
	s_cmp_lg_u32 s6, 1
	s_cbranch_scc1 .LBB0_200
	s_barrier

; __device__ __forceinline__ void grid_sync(cg::grid_group& grid) {
;     asm volatile("s_waitcnt vmcnt(0) lgkmcnt(0)" ::: "memory"); grid.sync();
;     __builtin_amdgcn_fence(__ATOMIC_ACQUIRE, "agent"); asm volatile("s_waitcnt vmcnt(0)" ::: "memory"); }
.LBB0_287:
	s_waitcnt vmcnt(0) lgkmcnt(0)
	s_barrier
	s_mov_b64 s[2:3], exec
	v_readlane_b32 s4, v253, 60
	v_readlane_b32 s5, v253, 61
	s_and_b64 s[4:5], s[2:3], s[4:5]
	s_mov_b64 exec, s[4:5]
	s_cbranch_execz .LBB0_297
	v_readlane_b32 s4, v249, 0
	v_readlane_b32 s5, v249, 1
	buffer_wbl2 sc1
	s_load_dwordx2 s[4:5], s[4:5], 0x58
	s_waitcnt vmcnt(0)
	s_mov_b64 s[6:7], exec
	v_mbcnt_lo_u32_b32 v1, s6, 0
	v_mbcnt_hi_u32_b32 v1, s7, v1
	v_cmp_eq_u32_e32 vcc, 0, v1
	s_waitcnt lgkmcnt(0)
	global_load_dword v0, v153, s[4:5] offset:40
	s_and_saveexec_b64 s[8:9], vcc
	s_cbranch_execz .LBB0_290
	s_bcnt1_i32_b64 s6, s[6:7]
	v_mov_b32_e32 v2, s6
	global_atomic_add v2, v153, v2, s[4:5] offset:32 sc0

; __device__ __forceinline__ void grid_sync(cg::grid_group& grid) {
;     asm volatile("s_waitcnt vmcnt(0) lgkmcnt(0)" ::: "memory"); grid.sync();
;     __builtin_amdgcn_fence(__ATOMIC_ACQUIRE, "agent"); asm volatile("s_waitcnt vmcnt(0)" ::: "memory"); }
.LBB0_771:
	s_or_b64 exec, exec, s[2:3]
	s_waitcnt vmcnt(0) lgkmcnt(0)
	s_waitcnt lgkmcnt(0)
	s_barrier
	s_mov_b64 s[2:3], exec
	v_readlane_b32 s4, v253, 60
	v_readlane_b32 s5, v253, 61
	s_and_b64 s[4:5], s[2:3], s[4:5]
	s_mov_b64 exec, s[4:5]
	s_cbranch_execz .LBB0_781
	v_readlane_b32 s4, v249, 0
	v_readlane_b32 s5, v249, 1
	buffer_wbl2 sc1
	s_load_dwordx2 s[4:5], s[4:5], 0x58
	s_waitcnt vmcnt(0)
	s_mov_b64 s[6:7], exec
	v_mbcnt_lo_u32_b32 v1, s6, 0
	v_mbcnt_hi_u32_b32 v1, s7, v1
	v_cmp_eq_u32_e32 vcc, 0, v1
	s_waitcnt lgkmcnt(0)
	global_load_dword v0, v153, s[4:5] offset:40
	s_and_saveexec_b64 s[8:9], vcc
	s_cbranch_execz .LBB0_774
	s_bcnt1_i32_b64 s6, s[6:7]
	v_mov_b32_e32 v2, s6
	global_atomic_add v2, v153, v2, s[4:5] offset:32 sc0

; __device__ __forceinline__ void grid_sync(cg::grid_group& grid) {
;     asm volatile("s_waitcnt vmcnt(0) lgkmcnt(0)" ::: "memory"); grid.sync();
;     __builtin_amdgcn_fence(__ATOMIC_ACQUIRE, "agent"); asm volatile("s_waitcnt vmcnt(0)" ::: "memory"); }
.LBB0_1041:
	v_readlane_b32 s4, v249, 0
	v_readlane_b32 s5, v249, 1
	buffer_wbl2 sc1
	s_load_dwordx2 s[4:5], s[4:5], 0x58
	s_waitcnt vmcnt(0)
	s_mov_b64 s[6:7], exec
	v_mbcnt_lo_u32_b32 v1, s6, 0
	v_mbcnt_hi_u32_b32 v1, s7, v1
	v_cmp_eq_u32_e32 vcc, 0, v1
	s_waitcnt lgkmcnt(0)
	global_load_dword v0, v153, s[4:5] offset:40
	s_and_saveexec_b64 s[8:9], vcc
	s_cbranch_execz .LBB0_1043
	s_bcnt1_i32_b64 s6, s[6:7]
	v_mov_b32_e32 v2, s6
	global_atomic_add v2, v153, v2, s[4:5] offset:32 sc0
